# mstate sample task: k and all 8 V fragment loads issued right after the gate wait (10 loads in flight, counted waits)
# baseline (speedup 1.0000x reference)
; #define LAS __attribute__((address_space(3)))
; __device__ __forceinline__ float fexp(float x) { return __builtin_amdgcn_exp2f(x * LOG2E); }
; #define LDS_WAIT() asm volatile("s_waitcnt lgkmcnt(0)" ::: "memory")
; __device__ __forceinline__ s16x8 pack8(const float (&x)[8]) { u32x4 p; p.x = pk2(x[0], x[1]); p.y = pk2(x[2], x[3]); p.z = pk2(x[4], x[5]); p.w = pk2(x[6], x[7]); return __builtin_bit_cast(s16x8, p); }
; __device__ __forceinline__ void unpack8(u32x4 v, float (&x)[8]) { x[0] = bflo(v.x); x[1] = bfhi(v.x); x[2] = bflo(v.y); x[3] = bfhi(v.y); x[4] = bflo(v.z); x[5] = bfhi(v.z); x[6] = bflo(v.w); x[7] = bfhi(v.w); }
;     __device__ __forceinline__ bf16* KVt() const { return (bf16*)(ws + WS_KVT); }
; template <bool SAMPLE>
; __device__ __forceinline__ void mstate_task(Ctx& C, int l, int unit, int h, int dblk, LAS float* wbuf) {
;     ...
;     const float li = valid ? C.GATES()[(grow0 + lane) * 8 + h] : -1e30f, lf = valid ? C.GATES()[(grow0 + lane) * 8 + 4 + h] : 0.f;
;     const float bc = scan_add(lf, lane), Bc = __shfl(bc, L - 1);
;     const float uu = valid ? Bc - bc + li : -1e30f, Mc = wave_max(uu);
;     const float w = valid ? fexp(uu - Mc) : 0.f;
;     wbuf[lane] = w;
;     LDS_WAIT();
;     const int d = 32 * dblk + r;
;     const bf16* krow = C.KVt() + (size_t)(R_KM + h * 128 + d) * MT + grow0;
;     float dn = 0.f; s16x8 Bf[NKS];
;     { u32x4 kq[NKS];
; #pragma unroll
;       for (int ks = 0; ks < NKS; ++ks) kq[ks] = *(const u32x4*)(krow + 16 * ks + 8 * hi);
; #pragma unroll
;       for (int ks = 0; ks < NKS; ++ks) { const int s0 = 16 * ks + 8 * hi;
;         float kc[8]; unpack8(kq[ks], kc);
;         const f32x4 w0 = *(const LAS f32x4*)(wbuf + s0), w1 = *(const LAS f32x4*)(wbuf + s0 + 4);
; #pragma unroll
;         for (int e = 0; e < 8; ++e) { kc[e] *= (e < 4 ? w0[e] : w1[e - 4]); dn += kc[e]; }
;         Bf[ks] = pack8(kc); } }
;     bf16* dcp = (SAMPLE ? C.DCS() + (size_t)(slot - NSLOT_P) * 16384 : C.DC() + (size_t)slot * 16384);
; #pragma unroll
;     for (int vb = 0; vb < 4; ++vb) {
;         f32x16 acc;
; #pragma unroll
;         for (int i = 0; i < 16; ++i) acc[i] = 0.f;
;         const bf16* vrow = C.KVt() + (size_t)(R_VM + h * 128 + 32 * vb + r) * MT + grow0 + 8 * hi;
;         s16x8 af[NKS];
; #pragma unroll
;         for (int ks = 0; ks < NKS; ++ks) af[ks] = *(const s16x8*)(vrow + 16 * ks);
.LBB0_633:
	s_or_b64 exec, exec, s[6:7]
	v_and_b32_e32 v0, 64, v220
	v_add_u32_e32 v3, -1, v220
	v_cmp_lt_i32_e32 vcc, v3, v0
	s_bfe_u32 s11, s23, 0x20006
	s_lshl_b32 s3, s10, 7
	v_cndmask_b32_e32 v3, v3, v220, vcc
	v_lshlrev_b32_e32 v3, 2, v3
	s_waitcnt vmcnt(0)
	ds_bpermute_b32 v3, v3, v1
	v_cmp_eq_u32_e32 vcc, 0, v40
	v_lshl_or_b32 v34, s11, 5, v42
	s_add_i32 s7, s3, 0x400
	s_lshl_b64 s[8:9], s[8:9], 1
	v_or_b32_e32 v84, s7, v34
	v_mov_b64_e32 v[86:87], s[74:75]
	s_add_u32 s40, s74, s8
	s_addc_u32 s41, s75, s9
	s_add_i32 s44, s3, 0x200
	v_mad_i64_i32 v[88:89], s[42:43], v84, s81, v[86:87]
	v_lshl_add_u64 v[88:89], v[88:89], 0, s[8:9]
	v_lshl_add_u64 v[88:89], v[88:89], 0, v[192:193]
	global_load_dwordx4 v[92:95], v[88:89], off
	global_load_dwordx4 v[96:99], v[88:89], off offset:32
	v_lshl_add_u64 v[90:91], s[40:41], 0, v[192:193]
	v_or_b32_e32 v85, s44, v42
	v_mad_i64_i32 v[64:65], s[42:43], v85, s81, v[90:91]
	v_or_b32_e32 v78, 32, v85
	v_mad_i64_i32 v[66:67], s[42:43], v78, s81, v[90:91]
	v_or_b32_e32 v78, 64, v85
	v_mad_i64_i32 v[68:69], s[42:43], v78, s81, v[90:91]
	v_or_b32_e32 v78, 0x60, v85
	v_mad_i64_i32 v[70:71], s[42:43], v78, s81, v[90:91]
	global_load_dwordx4 v[126:129], v[64:65], off
	global_load_dwordx4 v[130:133], v[64:65], off offset:32
	global_load_dwordx4 v[134:137], v[66:67], off
	global_load_dwordx4 v[138:141], v[66:67], off offset:32
	global_load_dwordx4 v[142:145], v[68:69], off
	global_load_dwordx4 v[146:149], v[68:69], off offset:32
	global_load_dwordx4 v[150:153], v[70:71], off
	global_load_dwordx4 v[154:157], v[70:71], off offset:32
	s_waitcnt lgkmcnt(0)
	v_add_f32_e32 v3, v1, v3
	v_cndmask_b32_e32 v1, v3, v1, vcc
	v_add_u32_e32 v3, -2, v220
	v_cmp_lt_i32_e32 vcc, v3, v0
	s_lshl_b32 s2, s2, 2
	s_add_i32 s6, s10, s2
	v_cndmask_b32_e32 v3, v3, v220, vcc
	v_lshlrev_b32_e32 v3, 2, v3
	ds_bpermute_b32 v3, v3, v1
	v_cmp_gt_u32_e32 vcc, 2, v40
	s_add_i32 s2, s6, 0x800
	v_readlane_b32 s10, v255, 3
	v_lshlrev_b32_e32 v26, 1, v34
	s_waitcnt lgkmcnt(0)
	v_add_f32_e32 v3, v1, v3
	v_cndmask_b32_e32 v1, v3, v1, vcc
	v_add_u32_e32 v3, -4, v220
	v_cmp_lt_i32_e32 vcc, v3, v0
	s_nop 1
	v_cndmask_b32_e32 v3, v3, v220, vcc
	v_lshlrev_b32_e32 v3, 2, v3
	ds_bpermute_b32 v3, v3, v1
	v_cmp_gt_u32_e32 vcc, 4, v40
	s_waitcnt lgkmcnt(0)
	v_add_f32_e32 v3, v1, v3
	v_cndmask_b32_e32 v1, v3, v1, vcc
	v_add_u32_e32 v3, -8, v220
	v_cmp_lt_i32_e32 vcc, v3, v0
	s_nop 1
	v_cndmask_b32_e32 v3, v3, v220, vcc
	v_lshlrev_b32_e32 v3, 2, v3
	ds_bpermute_b32 v3, v3, v1
	v_cmp_gt_u32_e32 vcc, 8, v40
	s_waitcnt lgkmcnt(0)
	v_add_f32_e32 v3, v1, v3
	v_cndmask_b32_e32 v1, v3, v1, vcc
	v_add_u32_e32 v3, -16, v220
	v_cmp_lt_i32_e32 vcc, v3, v0
	s_nop 1
	v_cndmask_b32_e32 v3, v3, v220, vcc
	v_lshlrev_b32_e32 v3, 2, v3
	ds_bpermute_b32 v3, v3, v1
	v_cmp_gt_u32_e32 vcc, 16, v40
	s_waitcnt lgkmcnt(0)
	v_add_f32_e32 v3, v1, v3
	v_cndmask_b32_e32 v1, v3, v1, vcc
	v_subrev_u32_e32 v3, 32, v220
	v_cmp_lt_i32_e32 vcc, v3, v0
	s_nop 1
	v_cndmask_b32_e32 v3, v3, v220, vcc
	v_lshlrev_b32_e32 v3, 2, v3
	ds_bpermute_b32 v3, v3, v1
	s_waitcnt lgkmcnt(0)
	v_add_f32_e32 v3, v1, v3
	v_cndmask_b32_e64 v1, v3, v1, s[4:5]
	v_lshlrev_b32_e32 v3, 2, v0
	ds_bpermute_b32 v32, v3, v1 offset:124
	v_add_u32_e32 v0, 64, v0
	v_xor_b32_e32 v3, 2, v220
	s_waitcnt lgkmcnt(0)
	v_sub_f32_e32 v1, v32, v1
	v_add_f32_e32 v1, v2, v1
	v_mov_b32_e32 v2, 0xf149f2ca
	v_cndmask_b32_e64 v1, v2, v1, s[4:5]
	v_xor_b32_e32 v2, 1, v220
	v_cmp_lt_i32_e32 vcc, v2, v0
	s_nop 1
	v_cndmask_b32_e32 v2, v220, v2, vcc
	v_lshlrev_b32_e32 v2, 2, v2
	ds_bpermute_b32 v2, v2, v1
	v_cmp_lt_i32_e32 vcc, v3, v0
	s_waitcnt lgkmcnt(0)
	v_max_f32_e32 v2, v2, v2
	v_cndmask_b32_e32 v3, v220, v3, vcc
	v_max_f32_e32 v2, v1, v2
	v_lshlrev_b32_e32 v3, 2, v3
	ds_bpermute_b32 v3, v3, v2
	s_waitcnt lgkmcnt(0)
	v_max_f32_e32 v3, v3, v3
	v_max_f32_e32 v2, v2, v3
	v_xor_b32_e32 v3, 4, v220
	v_cmp_lt_i32_e32 vcc, v3, v0
	s_nop 1
	v_cndmask_b32_e32 v3, v220, v3, vcc
	v_lshlrev_b32_e32 v3, 2, v3
	ds_bpermute_b32 v3, v3, v2
	s_waitcnt lgkmcnt(0)
	v_max_f32_e32 v3, v3, v3
	v_max_f32_e32 v2, v2, v3
	v_xor_b32_e32 v3, 8, v220
	v_cmp_lt_i32_e32 vcc, v3, v0
	s_nop 1
	v_cndmask_b32_e32 v3, v220, v3, vcc
	v_lshlrev_b32_e32 v3, 2, v3
	ds_bpermute_b32 v3, v3, v2
	s_waitcnt lgkmcnt(0)
	v_max_f32_e32 v3, v3, v3
	v_max_f32_e32 v2, v2, v3
	v_xor_b32_e32 v3, 16, v220
	v_cmp_lt_i32_e32 vcc, v3, v0
	s_nop 1
	v_cndmask_b32_e32 v3, v220, v3, vcc
	v_lshlrev_b32_e32 v3, 2, v3
	ds_bpermute_b32 v3, v3, v2
	s_waitcnt lgkmcnt(0)
	v_max_f32_e32 v3, v3, v3
	v_max_f32_e32 v2, v2, v3
	v_xor_b32_e32 v3, 32, v220
	v_cmp_lt_i32_e32 vcc, v3, v0
	s_nop 1
	v_cndmask_b32_e32 v0, v220, v3, vcc
	v_lshlrev_b32_e32 v35, 2, v0
	ds_bpermute_b32 v0, v35, v2
	s_waitcnt lgkmcnt(0)
	v_max_f32_e32 v0, v0, v0
	v_max_f32_e32 v33, v2, v0
	v_sub_f32_e32 v0, v1, v33
	v_mul_f32_e32 v0, 0x3fb8aa3b, v0
	v_exp_f32_e32 v0, v0
	v_or_b32_e32 v2, s7, v34
	s_ashr_i32 s7, s6, 31
	s_lshl_b64 s[6:7], s[6:7], 15
	v_cndmask_b32_e64 v0, 0, v0, s[4:5]
	ds_write_b32 v44, v0 offset:16384
	v_mov_b64_e32 v[0:1], s[74:75]
	v_mad_i64_i32 v[0:1], s[12:13], v2, s81, v[0:1]
	v_lshl_add_u64 v[0:1], v[0:1], 0, s[8:9]
	s_waitcnt lgkmcnt(0)
	v_lshl_add_u64 v[4:5], v[0:1], 0, v[192:193]
	s_waitcnt vmcnt(8)
	v_mov_b64_e32 v[0:1], v[92:93]
	v_mov_b64_e32 v[2:3], v[94:95]
	v_mov_b64_e32 v[4:5], v[96:97]
	v_mov_b64_e32 v[6:7], v[98:99]
	s_nop 0
	ds_read_b128 v[8:11], v43 offset:16384
	ds_read_b128 v[12:15], v43 offset:16400
	s_add_u32 s6, s10, s6
	v_readlane_b32 s10, v255, 4
	s_addc_u32 s7, s10, s7
	s_addk_i32 s3, 0x200
	s_add_u32 s8, s74, s8
	s_addc_u32 s9, s75, s9
	v_lshl_add_u64 v[28:29], s[8:9], 0, v[192:193]
	v_lshl_or_b32 v192, v41, 10, v26
	v_lshl_add_u64 v[26:27], s[6:7], 0, v[192:193]
	v_lshlrev_b32_e32 v16, 16, v0
	v_and_b32_e32 v17, 0xffff0000, v0
	s_waitcnt lgkmcnt(1)
; #define LAS __attribute__((address_space(3)))
; __device__ __forceinline__ bf16 f2bf(float f) { return (bf16)(pk2(f, 0.f) & 0xffffu); }
; #define MFMA32(a, b, c) __builtin_amdgcn_mfma_f32_32x32x16_bf16((a), (b), (c), 0, 0, 0)
; __device__ __forceinline__ s16x8 pack8(const float (&x)[8]) { u32x4 p; p.x = pk2(x[0], x[1]); p.y = pk2(x[2], x[3]); p.z = pk2(x[4], x[5]); p.w = pk2(x[6], x[7]); return __builtin_bit_cast(s16x8, p); }
; __device__ __forceinline__ void unpack8(u32x4 v, float (&x)[8]) { x[0] = bflo(v.x); x[1] = bfhi(v.x); x[2] = bflo(v.y); x[3] = bfhi(v.y); x[4] = bflo(v.z); x[5] = bfhi(v.z); x[6] = bflo(v.w); x[7] = bfhi(v.w); }
;     __device__ __forceinline__ bf16* KVt() const { return (bf16*)(ws + WS_KVT); }
;     __device__ __forceinline__ bf16* DC() const { return (bf16*)(ws + WS_XN); }
;     __device__ __forceinline__ bf16* DCS() const { return (bf16*)(ws + WS_DCS); }
; template <bool SAMPLE>
; __device__ __forceinline__ void mstate_task(Ctx& C, int l, int unit, int h, int dblk, LAS float* wbuf) {
;     ...
;     { u32x4 kq[NKS];
; #pragma unroll
;       for (int ks = 0; ks < NKS; ++ks) kq[ks] = *(const u32x4*)(krow + 16 * ks + 8 * hi);
; #pragma unroll
;       for (int ks = 0; ks < NKS; ++ks) { const int s0 = 16 * ks + 8 * hi;
;         float kc[8]; unpack8(kq[ks], kc);
;         const f32x4 w0 = *(const LAS f32x4*)(wbuf + s0), w1 = *(const LAS f32x4*)(wbuf + s0 + 4);
; #pragma unroll
;         for (int e = 0; e < 8; ++e) { kc[e] *= (e < 4 ? w0[e] : w1[e - 4]); dn += kc[e]; }
;         Bf[ks] = pack8(kc); } }
;     bf16* dcp = (SAMPLE ? C.DCS() + (size_t)(slot - NSLOT_P) * 16384 : C.DC() + (size_t)slot * 16384);
; #pragma unroll
;     for (int vb = 0; vb < 4; ++vb) {
;         f32x16 acc;
; #pragma unroll
;         for (int i = 0; i < 16; ++i) acc[i] = 0.f;
;         const bf16* vrow = C.KVt() + (size_t)(R_VM + h * 128 + 32 * vb + r) * MT + grow0 + 8 * hi;
;         s16x8 af[NKS];
; #pragma unroll
;         for (int ks = 0; ks < NKS; ++ks) af[ks] = *(const s16x8*)(vrow + 16 * ks);
; #pragma unroll
;         for (int ks = 0; ks < NKS; ++ks) acc = MFMA32(af[ks], Bf[ks], acc);
; #pragma unroll
;         for (int i = 0; i < 16; ++i) { const int v = 32 * vb + 8 * (i >> 2) + 4 * hi + (i & 3); dcp[v * 128 + d] = f2bf(acc[i]); }
	v_pk_mul_f32 v[8:9], v[8:9], v[16:17]
	s_nop 0
	v_add_f32_e32 v0, 0, v8
	v_add_f32_e32 v16, v9, v0
	v_lshlrev_b32_e32 v0, 16, v1
	v_and_b32_e32 v1, 0xffff0000, v1
	v_pk_mul_f32 v[0:1], v[10:11], v[0:1]
	v_and_b32_e32 v11, 0xffff0000, v2
	v_add_f32_e32 v10, v0, v16
	v_add_f32_e32 v16, v1, v10
	v_lshlrev_b32_e32 v10, 16, v2
	s_waitcnt lgkmcnt(0)
	v_pk_mul_f32 v[10:11], v[12:13], v[10:11]
	v_cvt_pk_bf16_f32 v17, v0, v1
	v_add_f32_e32 v2, v10, v16
	v_add_f32_e32 v12, v11, v2
	v_lshlrev_b32_e32 v2, 16, v3
	v_and_b32_e32 v3, 0xffff0000, v3
	v_pk_mul_f32 v[2:3], v[14:15], v[2:3]
	v_cvt_pk_bf16_f32 v16, v8, v9
	v_add_f32_e32 v12, v2, v12
	v_add_f32_e32 v14, v3, v12
	v_cvt_pk_bf16_f32 v18, v10, v11
	v_cvt_pk_bf16_f32 v19, v2, v3
	ds_read_b128 v[0:3], v43 offset:16448
	ds_read_b128 v[8:11], v43 offset:16464
	v_lshlrev_b32_e32 v12, 16, v4
	v_and_b32_e32 v13, 0xffff0000, v4
	s_waitcnt lgkmcnt(1)
	v_pk_mul_f32 v[0:1], v[0:1], v[12:13]
	s_nop 0
	v_add_f32_e32 v4, v0, v14
	v_add_f32_e32 v12, v1, v4
	v_lshlrev_b32_e32 v4, 16, v5
	v_and_b32_e32 v5, 0xffff0000, v5
	v_pk_mul_f32 v[2:3], v[2:3], v[4:5]
	v_and_b32_e32 v5, 0xffff0000, v6
	v_add_f32_e32 v4, v2, v12
	v_add_f32_e32 v12, v3, v4
	v_lshlrev_b32_e32 v4, 16, v6
	s_waitcnt lgkmcnt(0)
	v_pk_mul_f32 v[4:5], v[8:9], v[4:5]
	v_cvt_pk_bf16_f32 v20, v0, v1
	v_add_f32_e32 v6, v4, v12
	v_add_f32_e32 v8, v5, v6
	v_lshlrev_b32_e32 v6, 16, v7
	v_and_b32_e32 v7, 0xffff0000, v7
	v_pk_mul_f32 v[24:25], v[10:11], v[6:7]
	v_cvt_pk_bf16_f32 v22, v4, v5
	v_add_f32_e32 v36, v24, v8
	v_cvt_pk_bf16_f32 v23, v24, v25
	v_or_b32_e32 v24, s3, v42
	v_mad_i64_i32 v[4:5], s[8:9], v24, s81, v[28:29]
	v_cvt_pk_bf16_f32 v21, v2, v3
	s_movk_i32 s3, 0x4000
	s_waitcnt vmcnt(7)
	v_mfma_f32_32x32x16_bf16 v[0:15], v[126:129], v[16:19], 0
	s_waitcnt vmcnt(6)
	v_mfma_f32_32x32x16_bf16 v[0:15], v[130:133], v[20:23], v[0:15]
	s_nop 11
	v_cvt_pk_bf16_f32 v0, v0, s0
	global_store_short v192, v0, s[6:7]
	v_cvt_pk_bf16_f32 v0, v1, s0
	global_store_short v192, v0, s[6:7] offset:256
	v_cvt_pk_bf16_f32 v0, v2, s0
	global_store_short v192, v0, s[6:7] offset:512
	v_cvt_pk_bf16_f32 v0, v3, s0
	global_store_short v192, v0, s[6:7] offset:768
	v_cvt_pk_bf16_f32 v0, v4, s0
	global_store_short v192, v0, s[6:7] offset:2048
	v_cvt_pk_bf16_f32 v0, v5, s0
	global_store_short v192, v0, s[6:7] offset:2304
	v_cvt_pk_bf16_f32 v0, v6, s0
	global_store_short v192, v0, s[6:7] offset:2560
	v_cvt_pk_bf16_f32 v0, v7, s0
	global_store_short v192, v0, s[6:7] offset:2816
	v_add_co_u32_e32 v0, vcc, s60, v26
	v_cvt_pk_bf16_f32 v2, v8, s0
	s_nop 0
	v_addc_co_u32_e32 v1, vcc, 0, v27, vcc
	v_add_co_u32_e32 v30, vcc, s36, v26
	s_nop 1
	v_addc_co_u32_e32 v31, vcc, 0, v27, vcc
	global_store_short v[30:31], v2, off offset:-4096
	v_cvt_pk_bf16_f32 v2, v9, s0
	global_store_short v[0:1], v2, off offset:256
	v_cvt_pk_bf16_f32 v2, v10, s0
	global_store_short v[0:1], v2, off offset:512
	v_cvt_pk_bf16_f32 v2, v11, s0
	global_store_short v[0:1], v2, off offset:768
	v_cvt_pk_bf16_f32 v2, v12, s0
	global_store_short v[0:1], v2, off offset:2048
	v_cvt_pk_bf16_f32 v2, v13, s0
	global_store_short v[0:1], v2, off offset:2304
	v_cvt_pk_bf16_f32 v2, v14, s0
	global_store_short v[0:1], v2, off offset:2560
	v_cvt_pk_bf16_f32 v2, v15, s0
	global_store_short v[0:1], v2, off offset:2816
	v_or_b32_e32 v0, 32, v24
	v_mad_i64_i32 v[4:5], s[6:7], v0, s81, v[28:29]
	s_waitcnt vmcnt(21)
	v_mfma_f32_32x32x16_bf16 v[0:15], v[134:137], v[16:19], 0
	s_waitcnt vmcnt(20)
	v_mfma_f32_32x32x16_bf16 v[0:15], v[138:141], v[20:23], v[0:15]
	s_nop 11
	v_cvt_pk_bf16_f32 v0, v0, s0
	global_store_short v[30:31], v0, off
	v_cvt_pk_bf16_f32 v0, v1, s0
	global_store_short v[30:31], v0, off offset:256
	v_cvt_pk_bf16_f32 v0, v2, s0
	global_store_short v[30:31], v0, off offset:512
	v_cvt_pk_bf16_f32 v0, v3, s0
	global_store_short v[30:31], v0, off offset:768
	v_cvt_pk_bf16_f32 v0, v4, s0
	global_store_short v[30:31], v0, off offset:2048
	v_cvt_pk_bf16_f32 v0, v5, s0
	global_store_short v[30:31], v0, off offset:2304
	v_cvt_pk_bf16_f32 v0, v6, s0
	global_store_short v[30:31], v0, off offset:2560
	v_cvt_pk_bf16_f32 v0, v7, s0
	global_store_short v[30:31], v0, off offset:2816
	v_add_co_u32_e32 v0, vcc, s38, v26
	v_cvt_pk_bf16_f32 v2, v8, s0
	s_nop 0
	v_addc_co_u32_e32 v1, vcc, 0, v27, vcc
	v_add_co_u32_e32 v30, vcc, s3, v26
	s_movk_i32 s3, 0x7000
	s_nop 0
	v_addc_co_u32_e32 v31, vcc, 0, v27, vcc
	global_store_short v[30:31], v2, off offset:-4096
	v_cvt_pk_bf16_f32 v2, v9, s0
	global_store_short v[0:1], v2, off offset:256
	v_cvt_pk_bf16_f32 v2, v10, s0
	global_store_short v[0:1], v2, off offset:512
	v_cvt_pk_bf16_f32 v2, v11, s0
	global_store_short v[0:1], v2, off offset:768
	v_cvt_pk_bf16_f32 v2, v12, s0
	global_store_short v[0:1], v2, off offset:2048
	v_cvt_pk_bf16_f32 v2, v13, s0
	global_store_short v[0:1], v2, off offset:2304
	v_cvt_pk_bf16_f32 v2, v14, s0
	global_store_short v[0:1], v2, off offset:2560
	v_cvt_pk_bf16_f32 v2, v15, s0
	global_store_short v[0:1], v2, off offset:2816
	v_or_b32_e32 v0, 64, v24
	v_mad_i64_i32 v[4:5], s[6:7], v0, s81, v[28:29]
	s_waitcnt vmcnt(35)
; __device__ __forceinline__ bf16 f2bf(float f) { return (bf16)(pk2(f, 0.f) & 0xffffu); }
; #define MFMA32(a, b, c) __builtin_amdgcn_mfma_f32_32x32x16_bf16((a), (b), (c), 0, 0, 0)
;     __device__ __forceinline__ float* DN() const { return (float*)(ws + WS_DN); }
; template <bool SAMPLE>
; __device__ __forceinline__ void mstate_task(Ctx& C, int l, int unit, int h, int dblk, LAS float* wbuf) {
;     ...
;         for (int ks = 0; ks < NKS; ++ks) af[ks] = *(const s16x8*)(vrow + 16 * ks);
; #pragma unroll
;         for (int ks = 0; ks < NKS; ++ks) acc = MFMA32(af[ks], Bf[ks], acc);
; #pragma unroll
;         for (int i = 0; i < 16; ++i) { const int v = 32 * vb + 8 * (i >> 2) + 4 * hi + (i & 3); dcp[v * 128 + d] = f2bf(acc[i]); }
;     }
;     dn += __shfl_xor(dn, 32);
;     if (hi == 0) C.DN()[(size_t)slot * 128 + d] = dn;
	v_mfma_f32_32x32x16_bf16 v[0:15], v[142:145], v[16:19], 0
	s_waitcnt vmcnt(34)
	v_mfma_f32_32x32x16_bf16 v[0:15], v[146:149], v[20:23], v[0:15]
	s_nop 11
	v_cvt_pk_bf16_f32 v0, v0, s0
	global_store_short v[30:31], v0, off
	v_cvt_pk_bf16_f32 v0, v1, s0
	global_store_short v[30:31], v0, off offset:256
	v_cvt_pk_bf16_f32 v0, v2, s0
	global_store_short v[30:31], v0, off offset:512
	v_cvt_pk_bf16_f32 v0, v3, s0
	global_store_short v[30:31], v0, off offset:768
	v_cvt_pk_bf16_f32 v0, v4, s0
	global_store_short v[30:31], v0, off offset:2048
	v_cvt_pk_bf16_f32 v0, v5, s0
	global_store_short v[30:31], v0, off offset:2304
	v_cvt_pk_bf16_f32 v0, v6, s0
	global_store_short v[30:31], v0, off offset:2560
	v_cvt_pk_bf16_f32 v0, v7, s0
	global_store_short v[30:31], v0, off offset:2816
	v_add_co_u32_e32 v0, vcc, s35, v26
	v_cvt_pk_bf16_f32 v2, v8, s0
	s_nop 0
	v_addc_co_u32_e32 v1, vcc, 0, v27, vcc
	v_add_co_u32_e32 v30, vcc, s93, v26
	s_nop 1
	v_addc_co_u32_e32 v31, vcc, 0, v27, vcc
	global_store_short v[30:31], v2, off offset:-4096
	v_cvt_pk_bf16_f32 v2, v9, s0
	global_store_short v[0:1], v2, off offset:256
	v_cvt_pk_bf16_f32 v2, v10, s0
	global_store_short v[0:1], v2, off offset:512
	v_cvt_pk_bf16_f32 v2, v11, s0
	global_store_short v[0:1], v2, off offset:768
	v_cvt_pk_bf16_f32 v2, v12, s0
	global_store_short v[0:1], v2, off offset:2048
	v_cvt_pk_bf16_f32 v2, v13, s0
	global_store_short v[0:1], v2, off offset:2304
	v_cvt_pk_bf16_f32 v2, v14, s0
	global_store_short v[0:1], v2, off offset:2560
	v_cvt_pk_bf16_f32 v2, v15, s0
	global_store_short v[0:1], v2, off offset:2816
	v_or_b32_e32 v0, 0x60, v24
	v_mad_i64_i32 v[4:5], s[6:7], v0, s81, v[28:29]
	s_waitcnt vmcnt(49)
	v_mfma_f32_32x32x16_bf16 v[0:15], v[150:153], v[16:19], 0
	s_waitcnt vmcnt(48)
	v_mfma_f32_32x32x16_bf16 v[0:15], v[154:157], v[20:23], v[0:15]
	s_nop 11
	v_cvt_pk_bf16_f32 v0, v0, s0
	global_store_short v[30:31], v0, off
	v_cvt_pk_bf16_f32 v0, v1, s0
	global_store_short v[30:31], v0, off offset:256
	v_cvt_pk_bf16_f32 v0, v2, s0
	global_store_short v[30:31], v0, off offset:512
	v_cvt_pk_bf16_f32 v0, v3, s0
	global_store_short v[30:31], v0, off offset:768
	v_cvt_pk_bf16_f32 v0, v4, s0
	global_store_short v[30:31], v0, off offset:2048
	v_cvt_pk_bf16_f32 v0, v5, s0
	global_store_short v[30:31], v0, off offset:2304
	v_cvt_pk_bf16_f32 v0, v6, s0
	global_store_short v[30:31], v0, off offset:2560
	v_cvt_pk_bf16_f32 v0, v7, s0
	global_store_short v[30:31], v0, off offset:2816
	v_add_co_u32_e32 v0, vcc, s3, v26
	v_cvt_pk_bf16_f32 v2, v8, s0
	s_nop 0
	v_addc_co_u32_e32 v1, vcc, 0, v27, vcc
	global_store_short v[0:1], v2, off
	v_cvt_pk_bf16_f32 v2, v9, s0
	global_store_short v[0:1], v2, off offset:256
	v_cvt_pk_bf16_f32 v2, v10, s0
	global_store_short v[0:1], v2, off offset:512
	v_cvt_pk_bf16_f32 v2, v11, s0
	global_store_short v[0:1], v2, off offset:768
	v_cvt_pk_bf16_f32 v2, v12, s0
	global_store_short v[0:1], v2, off offset:2048
	v_cvt_pk_bf16_f32 v2, v13, s0
	global_store_short v[0:1], v2, off offset:2304
	v_cvt_pk_bf16_f32 v2, v14, s0
	global_store_short v[0:1], v2, off offset:2560
	v_cvt_pk_bf16_f32 v2, v15, s0
	global_store_short v[0:1], v2, off offset:2816
	v_add_f32_e32 v0, v25, v36
	ds_bpermute_b32 v1, v35, v0
	s_and_saveexec_b64 s[6:7], s[4:5]
	s_cbranch_execz .LBB0_635
	s_ashr_i32 s3, s2, 31
	s_lshl_b64 s[4:5], s[2:3], 9
	v_readlane_b32 s8, v254, 61
	v_readlane_b32 s9, v254, 62
	s_add_u32 s4, s8, s4
	s_waitcnt lgkmcnt(0)
	v_add_f32_e32 v0, v0, v1
	s_addc_u32 s5, s9, s5
	v_lshlrev_b32_e32 v1, 2, v34
	global_store_dword v1, v0, s[4:5]
